# indexer radix-select count: v_cmp_lt_u32 + v_addc_co_u32 per value with three rotating mask registers (2 VALU per value instead of 3.5), cross-row sum by v_permlane16_swap instead of ds_bpermute
# speedup vs baseline: 1.0248x; 1.0085x over previous
; DI void indexer_phase(const u16* __restrict__ P, unsigned* __restrict__ mask) {
;     ...
;       const unsigned Tp = T | (1u << bit);
;       int cnt = 0;
; #pragma unroll
;       for (int kb = 0; kb < 64; ++kb) cnt += (sc[kb] >= Tp) ? 1 : 0;
; #pragma unroll
;       for (int o = 16; o; o >>= 1) cnt += __shfl_xor(cnt, o);
;       if (cnt >= target) T = Tp;
;     }
.Lsel_g7:
	v_cmp_lt_u32_e32 vcc, v205, v9
	v_cmp_lt_u32_e64 s[36:37], v236, v9
	v_cmp_lt_u32_e64 s[38:39], v207, v9
	v_addc_co_u32_e32 v10, vcc, 0, v10, vcc
	v_cmp_lt_u32_e32 vcc, v238, v9
	v_addc_co_u32_e64 v11, s[36:37], 0, v11, s[36:37]
	v_cmp_lt_u32_e64 s[36:37], v237, v9
	v_addc_co_u32_e64 v10, s[38:39], 0, v10, s[38:39]
	v_cmp_lt_u32_e64 s[38:39], v240, v9
	v_addc_co_u32_e32 v11, vcc, 0, v11, vcc
	v_cmp_lt_u32_e32 vcc, v239, v9
	v_addc_co_u32_e64 v10, s[36:37], 0, v10, s[36:37]
	v_cmp_lt_u32_e64 s[36:37], v18, v9
	v_addc_co_u32_e64 v11, s[38:39], 0, v11, s[38:39]
	v_addc_co_u32_e32 v10, vcc, 0, v10, vcc
	v_addc_co_u32_e64 v11, s[36:37], 0, v11, s[36:37]
.Lsel_g6:
	v_cmp_lt_u32_e32 vcc, v197, v9
	v_cmp_lt_u32_e64 s[36:37], v200, v9
	v_cmp_lt_u32_e64 s[38:39], v199, v9
	v_addc_co_u32_e32 v10, vcc, 0, v10, vcc
	v_cmp_lt_u32_e32 vcc, v202, v9
	v_addc_co_u32_e64 v11, s[36:37], 0, v11, s[36:37]
	v_cmp_lt_u32_e64 s[36:37], v201, v9
	v_addc_co_u32_e64 v10, s[38:39], 0, v10, s[38:39]
	v_cmp_lt_u32_e64 s[38:39], v204, v9
	v_addc_co_u32_e32 v11, vcc, 0, v11, vcc
	v_cmp_lt_u32_e32 vcc, v203, v9
	v_addc_co_u32_e64 v10, s[36:37], 0, v10, s[36:37]
	v_cmp_lt_u32_e64 s[36:37], v206, v9
	v_addc_co_u32_e64 v11, s[38:39], 0, v11, s[38:39]
	v_addc_co_u32_e32 v10, vcc, 0, v10, vcc
	v_addc_co_u32_e64 v11, s[36:37], 0, v11, s[36:37]
.Lsel_g5:
	v_cmp_lt_u32_e32 vcc, v189, v9
	v_cmp_lt_u32_e64 s[36:37], v192, v9
	v_cmp_lt_u32_e64 s[38:39], v191, v9
	v_addc_co_u32_e32 v10, vcc, 0, v10, vcc
	v_cmp_lt_u32_e32 vcc, v194, v9
	v_addc_co_u32_e64 v11, s[36:37], 0, v11, s[36:37]
	v_cmp_lt_u32_e64 s[36:37], v193, v9
	v_addc_co_u32_e64 v10, s[38:39], 0, v10, s[38:39]
	v_cmp_lt_u32_e64 s[38:39], v196, v9
	v_addc_co_u32_e32 v11, vcc, 0, v11, vcc
	v_cmp_lt_u32_e32 vcc, v195, v9
	v_addc_co_u32_e64 v10, s[36:37], 0, v10, s[36:37]
	v_cmp_lt_u32_e64 s[36:37], v198, v9
	v_addc_co_u32_e64 v11, s[38:39], 0, v11, s[38:39]
	v_addc_co_u32_e32 v10, vcc, 0, v10, vcc
	v_addc_co_u32_e64 v11, s[36:37], 0, v11, s[36:37]
.Lsel_g4:
	v_cmp_lt_u32_e32 vcc, v175, v9
	v_cmp_lt_u32_e64 s[36:37], v184, v9
	v_cmp_lt_u32_e64 s[38:39], v183, v9
	v_addc_co_u32_e32 v10, vcc, 0, v10, vcc
	v_cmp_lt_u32_e32 vcc, v186, v9
	v_addc_co_u32_e64 v11, s[36:37], 0, v11, s[36:37]
	v_cmp_lt_u32_e64 s[36:37], v185, v9
	v_addc_co_u32_e64 v10, s[38:39], 0, v10, s[38:39]
	v_cmp_lt_u32_e64 s[38:39], v188, v9
	v_addc_co_u32_e32 v11, vcc, 0, v11, vcc
	v_cmp_lt_u32_e32 vcc, v187, v9
	v_addc_co_u32_e64 v10, s[36:37], 0, v10, s[36:37]
	v_cmp_lt_u32_e64 s[36:37], v190, v9
	v_addc_co_u32_e64 v11, s[38:39], 0, v11, s[38:39]
	v_addc_co_u32_e32 v10, vcc, 0, v10, vcc
	v_addc_co_u32_e64 v11, s[36:37], 0, v11, s[36:37]
.Lsel_g3:
	v_cmp_lt_u32_e32 vcc, v167, v9
	v_cmp_lt_u32_e64 s[36:37], v170, v9
	v_cmp_lt_u32_e64 s[38:39], v169, v9
	v_addc_co_u32_e32 v10, vcc, 0, v10, vcc
	v_cmp_lt_u32_e32 vcc, v172, v9
	v_addc_co_u32_e64 v11, s[36:37], 0, v11, s[36:37]
	v_cmp_lt_u32_e64 s[36:37], v171, v9
	v_addc_co_u32_e64 v10, s[38:39], 0, v10, s[38:39]
	v_cmp_lt_u32_e64 s[38:39], v174, v9
	v_addc_co_u32_e32 v11, vcc, 0, v11, vcc
	v_cmp_lt_u32_e32 vcc, v173, v9
	v_addc_co_u32_e64 v10, s[36:37], 0, v10, s[36:37]
	v_cmp_lt_u32_e64 s[36:37], v182, v9
	v_addc_co_u32_e64 v11, s[38:39], 0, v11, s[38:39]
	v_addc_co_u32_e32 v10, vcc, 0, v10, vcc
	v_addc_co_u32_e64 v11, s[36:37], 0, v11, s[36:37]
.Lsel_g2:
	v_cmp_lt_u32_e32 vcc, v159, v9
	v_cmp_lt_u32_e64 s[36:37], v162, v9
	v_cmp_lt_u32_e64 s[38:39], v161, v9
	v_addc_co_u32_e32 v10, vcc, 0, v10, vcc
	v_cmp_lt_u32_e32 vcc, v164, v9
	v_addc_co_u32_e64 v11, s[36:37], 0, v11, s[36:37]
	v_cmp_lt_u32_e64 s[36:37], v163, v9
	v_addc_co_u32_e64 v10, s[38:39], 0, v10, s[38:39]
	v_cmp_lt_u32_e64 s[38:39], v166, v9
	v_addc_co_u32_e32 v11, vcc, 0, v11, vcc
	v_cmp_lt_u32_e32 vcc, v165, v9
	v_addc_co_u32_e64 v10, s[36:37], 0, v10, s[36:37]
	v_cmp_lt_u32_e64 s[36:37], v168, v9
	v_addc_co_u32_e64 v11, s[38:39], 0, v11, s[38:39]
	v_addc_co_u32_e32 v10, vcc, 0, v10, vcc
	v_addc_co_u32_e64 v11, s[36:37], 0, v11, s[36:37]
.Lsel_g1:
	v_cmp_lt_u32_e32 vcc, v151, v9
	v_cmp_lt_u32_e64 s[36:37], v154, v9
	v_cmp_lt_u32_e64 s[38:39], v153, v9
	v_addc_co_u32_e32 v10, vcc, 0, v10, vcc
	v_cmp_lt_u32_e32 vcc, v156, v9
	v_addc_co_u32_e64 v11, s[36:37], 0, v11, s[36:37]
	v_cmp_lt_u32_e64 s[36:37], v155, v9
	v_addc_co_u32_e64 v10, s[38:39], 0, v10, s[38:39]
	v_cmp_lt_u32_e64 s[38:39], v158, v9
	v_addc_co_u32_e32 v11, vcc, 0, v11, vcc
	v_cmp_lt_u32_e32 vcc, v157, v9
	v_addc_co_u32_e64 v10, s[36:37], 0, v10, s[36:37]
	v_cmp_lt_u32_e64 s[36:37], v160, v9
	v_addc_co_u32_e64 v11, s[38:39], 0, v11, s[38:39]
	v_addc_co_u32_e32 v10, vcc, 0, v10, vcc
	v_addc_co_u32_e64 v11, s[36:37], 0, v11, s[36:37]
; DI void indexer_phase(const u16* __restrict__ P, unsigned* __restrict__ mask) {
;     ...
; #pragma unroll
;       for (int kb = 0; kb < 64; ++kb) cnt += (sc[kb] >= Tp) ? 1 : 0;
; #pragma unroll
;       for (int o = 16; o; o >>= 1) cnt += __shfl_xor(cnt, o);
;       if (cnt >= target) T = Tp;
;     }
;     unsigned w0 = 0u, w1 = 0u;
; #pragma unroll
;     for (int kb = 0; kb < 64; ++kb) {
;       const bool pred = (sc[kb] >= T) && (sc[kb] != 0u);
;       const unsigned long long bal = __ballot(pred);
;       const unsigned wd = (unsigned)(bal >> (32 * hi));
;       if ((kb & 31) == r32) { if (kb < 32) w0 = wd; else w1 = wd; }
;     }
.Lsel_g0:
	v_cmp_lt_u32_e32 vcc, v2, v9
	v_cmp_lt_u32_e64 s[36:37], v146, v9
	v_cmp_lt_u32_e64 s[38:39], v145, v9
	v_addc_co_u32_e32 v10, vcc, 0, v10, vcc
	v_cmp_lt_u32_e32 vcc, v148, v9
	v_addc_co_u32_e64 v11, s[36:37], 0, v11, s[36:37]
	v_cmp_lt_u32_e64 s[36:37], v147, v9
	v_addc_co_u32_e64 v10, s[38:39], 0, v10, s[38:39]
	v_cmp_lt_u32_e64 s[38:39], v150, v9
	v_addc_co_u32_e32 v11, vcc, 0, v11, vcc
	v_cmp_lt_u32_e32 vcc, v149, v9
	v_addc_co_u32_e64 v10, s[36:37], 0, v10, s[36:37]
	v_cmp_lt_u32_e64 s[36:37], v152, v9
	v_addc_co_u32_e64 v11, s[38:39], 0, v11, s[38:39]
	v_addc_co_u32_e32 v10, vcc, 0, v10, vcc
	v_addc_co_u32_e64 v11, s[36:37], 0, v11, s[36:37]
	v_add_u32_e32 v10, v10, v11
	v_sub_u32_e32 v10, s72, v10
	v_mov_b32_e32 v11, v10
	s_nop 1
	v_permlane16_swap_b32_e32 v11, v10
	v_add_u32_e32 v10, v10, v11
	s_nop 1
	v_add_u32_dpp v10, v10, v10 quad_perm:[1,0,3,2] row_mask:0xf bank_mask:0xf
	s_nop 1
	v_add_u32_dpp v10, v10, v10 quad_perm:[2,3,0,1] row_mask:0xf bank_mask:0xf
	s_nop 1
	v_add_u32_dpp v10, v10, v10 row_half_mirror row_mask:0xf bank_mask:0xf
	s_nop 1
	v_add_u32_dpp v10, v10, v10 row_mirror row_mask:0xf bank_mask:0xf
	v_cmp_gt_i32_e32 vcc, v10, v3
	s_cmp_eq_u32 s0, -1
	s_nop 0
	v_cndmask_b32_e32 v144, v144, v9, vcc
	s_cbranch_scc0 .LBB0_974
	v_cmp_ge_u32_e32 vcc, v2, v144
	v_cmp_ne_u32_e64 s[0:1], 0, v2
	s_and_b64 s[0:1], s[0:1], vcc
	v_readlane_b32 s36, v254, 56
	v_cndmask_b32_e64 v2, 0, 1, s[0:1]
	v_cmp_ne_u32_e32 vcc, 0, v2
	v_cmp_ne_u32_e64 s[0:1], 0, v146
	v_readlane_b32 s37, v254, 57
	v_lshrrev_b64 v[2:3], v56, vcc
	v_cmp_ge_u32_e32 vcc, v146, v144
	s_and_b64 s[0:1], s[0:1], vcc
	v_cndmask_b32_e64 v4, 0, v2, s[36:37]
	v_cndmask_b32_e64 v2, 0, 1, s[0:1]
	v_cmp_ne_u32_e32 vcc, 0, v2
	v_readlane_b32 s38, v254, 58
	v_cmp_ne_u32_e64 s[0:1], 0, v145
	v_lshrrev_b64 v[2:3], v56, vcc
	v_cmp_ge_u32_e32 vcc, v145, v144
	v_readlane_b32 s39, v254, 59
	s_and_b64 s[0:1], s[0:1], vcc
	v_readlane_b32 s40, v254, 60
	v_cndmask_b32_e64 v4, v4, v2, s[38:39]
	v_cndmask_b32_e64 v2, 0, 1, s[0:1]
	v_cmp_ne_u32_e32 vcc, 0, v2
	v_cmp_ne_u32_e64 s[0:1], 0, v148
	v_readlane_b32 s41, v254, 61
	v_lshrrev_b64 v[2:3], v56, vcc
	v_cmp_ge_u32_e32 vcc, v148, v144
	s_and_b64 s[0:1], s[0:1], vcc
	v_cndmask_b32_e64 v4, v4, v2, s[40:41]
	v_cndmask_b32_e64 v2, 0, 1, s[0:1]
	v_cmp_ne_u32_e32 vcc, 0, v2
	v_readlane_b32 s44, v254, 62
	v_cmp_ne_u32_e64 s[0:1], 0, v147
	v_lshrrev_b64 v[2:3], v56, vcc
	v_cmp_ge_u32_e32 vcc, v147, v144
	v_readlane_b32 s45, v254, 63
	s_and_b64 s[0:1], s[0:1], vcc
	v_readlane_b32 s46, v255, 0
	v_cndmask_b32_e64 v4, v4, v2, s[44:45]
	v_cndmask_b32_e64 v2, 0, 1, s[0:1]
	v_cmp_ne_u32_e32 vcc, 0, v2
	v_cmp_ne_u32_e64 s[0:1], 0, v150
	v_readlane_b32 s47, v255, 1
	v_lshrrev_b64 v[2:3], v56, vcc
	v_cmp_ge_u32_e32 vcc, v150, v144
	s_and_b64 s[0:1], s[0:1], vcc
	v_cndmask_b32_e64 v4, v4, v2, s[46:47]
	v_cndmask_b32_e64 v2, 0, 1, s[0:1]
	v_cmp_ne_u32_e32 vcc, 0, v2
	v_readlane_b32 s48, v255, 2
	v_cmp_ne_u32_e64 s[0:1], 0, v149
	v_lshrrev_b64 v[2:3], v56, vcc
	v_cmp_ge_u32_e32 vcc, v149, v144
	v_readlane_b32 s49, v255, 3
	s_and_b64 s[0:1], s[0:1], vcc
	v_readlane_b32 s50, v255, 4
	v_cndmask_b32_e64 v4, v4, v2, s[48:49]
	v_cndmask_b32_e64 v2, 0, 1, s[0:1]
	v_cmp_ne_u32_e32 vcc, 0, v2
	v_cmp_ne_u32_e64 s[0:1], 0, v152
	v_readlane_b32 s51, v255, 5
	v_lshrrev_b64 v[2:3], v56, vcc
	v_cmp_ge_u32_e32 vcc, v152, v144
	s_and_b64 s[0:1], s[0:1], vcc
	v_cndmask_b32_e64 v4, v4, v2, s[50:51]
	v_cndmask_b32_e64 v2, 0, 1, s[0:1]
	v_cmp_ne_u32_e32 vcc, 0, v2
	v_readlane_b32 s18, v255, 6
	v_cmp_ne_u32_e64 s[0:1], 0, v151
	v_lshrrev_b64 v[2:3], v56, vcc
	v_cmp_ge_u32_e32 vcc, v151, v144
	v_readlane_b32 s19, v255, 7
	s_and_b64 s[0:1], s[0:1], vcc
	v_readlane_b32 s22, v255, 8
	v_cndmask_b32_e64 v4, v4, v2, s[18:19]
	v_cndmask_b32_e64 v2, 0, 1, s[0:1]
	v_cmp_ne_u32_e32 vcc, 0, v2
	v_cmp_ne_u32_e64 s[0:1], 0, v154
	v_readlane_b32 s23, v255, 9
	v_lshrrev_b64 v[2:3], v56, vcc
	v_cmp_ge_u32_e32 vcc, v154, v144
	s_and_b64 s[0:1], s[0:1], vcc
	v_cndmask_b32_e64 v4, v4, v2, s[22:23]
	v_cndmask_b32_e64 v2, 0, 1, s[0:1]
	v_cmp_ne_u32_e32 vcc, 0, v2
	v_readlane_b32 s24, v255, 10
	v_cmp_ne_u32_e64 s[0:1], 0, v153
	v_lshrrev_b64 v[2:3], v56, vcc
	v_cmp_ge_u32_e32 vcc, v153, v144
	v_readlane_b32 s25, v255, 11
	s_and_b64 s[0:1], s[0:1], vcc
	v_readlane_b32 s26, v255, 12
	v_cndmask_b32_e64 v4, v4, v2, s[24:25]
	v_cndmask_b32_e64 v2, 0, 1, s[0:1]
	v_cmp_ne_u32_e32 vcc, 0, v2
	v_cmp_ne_u32_e64 s[0:1], 0, v156
	v_readlane_b32 s27, v255, 13
	v_lshrrev_b64 v[2:3], v56, vcc
	v_cmp_ge_u32_e32 vcc, v156, v144
	s_and_b64 s[0:1], s[0:1], vcc
	v_cndmask_b32_e64 v4, v4, v2, s[26:27]
	v_cndmask_b32_e64 v2, 0, 1, s[0:1]
	v_cmp_ne_u32_e32 vcc, 0, v2
	v_readlane_b32 s30, v255, 14
	v_cmp_ne_u32_e64 s[0:1], 0, v155
	v_lshrrev_b64 v[2:3], v56, vcc
	v_cmp_ge_u32_e32 vcc, v155, v144
	v_readlane_b32 s31, v255, 15
	s_and_b64 s[0:1], s[0:1], vcc
	v_readlane_b32 s8, v255, 16
	v_cndmask_b32_e64 v4, v4, v2, s[30:31]
	v_cndmask_b32_e64 v2, 0, 1, s[0:1]
	v_cmp_ne_u32_e32 vcc, 0, v2
	v_cmp_ne_u32_e64 s[0:1], 0, v158
	v_readlane_b32 s9, v255, 17
	v_lshrrev_b64 v[2:3], v56, vcc
	v_cmp_ge_u32_e32 vcc, v158, v144
	s_and_b64 s[0:1], s[0:1], vcc
	v_cndmask_b32_e64 v4, v4, v2, s[8:9]
	v_cndmask_b32_e64 v2, 0, 1, s[0:1]
	v_cmp_ne_u32_e32 vcc, 0, v2
	v_readlane_b32 s10, v255, 18
	v_cmp_ne_u32_e64 s[0:1], 0, v157
	v_lshrrev_b64 v[2:3], v56, vcc
	v_cmp_ge_u32_e32 vcc, v157, v144
	v_readlane_b32 s11, v255, 19
	s_and_b64 s[0:1], s[0:1], vcc
	v_readlane_b32 s12, v255, 20
	v_cndmask_b32_e64 v4, v4, v2, s[10:11]
	v_cndmask_b32_e64 v2, 0, 1, s[0:1]
	v_cmp_ne_u32_e32 vcc, 0, v2
	v_cmp_ne_u32_e64 s[0:1], 0, v160
; DI void indexer_phase(const u16* __restrict__ P, unsigned* __restrict__ mask) {
;     ...
;     unsigned w0 = 0u, w1 = 0u;
; #pragma unroll
;     for (int kb = 0; kb < 64; ++kb) {
;       const bool pred = (sc[kb] >= T) && (sc[kb] != 0u);
;       const unsigned long long bal = __ballot(pred);
;       const unsigned wd = (unsigned)(bal >> (32 * hi));
;       if ((kb & 31) == r32) { if (kb < 32) w0 = wd; else w1 = wd; }
;     }
	v_readlane_b32 s13, v255, 21
	v_lshrrev_b64 v[2:3], v56, vcc
	v_cmp_ge_u32_e32 vcc, v160, v144
	s_and_b64 s[0:1], s[0:1], vcc
	v_cndmask_b32_e64 v4, v4, v2, s[12:13]
	v_cndmask_b32_e64 v2, 0, 1, s[0:1]
	v_cmp_ne_u32_e32 vcc, 0, v2
	v_readlane_b32 s14, v255, 22
	v_cmp_ne_u32_e64 s[0:1], 0, v159
	v_lshrrev_b64 v[2:3], v56, vcc
	v_cmp_ge_u32_e32 vcc, v159, v144
	v_readlane_b32 s15, v255, 23
	s_and_b64 s[0:1], s[0:1], vcc
	v_readlane_b32 s66, v255, 24
	v_cndmask_b32_e64 v4, v4, v2, s[14:15]
	v_cndmask_b32_e64 v2, 0, 1, s[0:1]
	v_cmp_ne_u32_e32 vcc, 0, v2
	v_cmp_ne_u32_e64 s[0:1], 0, v162
	v_readlane_b32 s67, v255, 25
	v_lshrrev_b64 v[2:3], v56, vcc
	v_cmp_ge_u32_e32 vcc, v162, v144
	s_and_b64 s[0:1], s[0:1], vcc
	v_cndmask_b32_e64 v4, v4, v2, s[66:67]
	v_cndmask_b32_e64 v2, 0, 1, s[0:1]
	v_cmp_ne_u32_e32 vcc, 0, v2
	v_readlane_b32 s68, v255, 26
	v_cmp_ne_u32_e64 s[0:1], 0, v161
	v_lshrrev_b64 v[2:3], v56, vcc
	v_cmp_ge_u32_e32 vcc, v161, v144
	v_readlane_b32 s69, v255, 27
	s_and_b64 s[0:1], s[0:1], vcc
	v_readlane_b32 s70, v255, 28
	v_cndmask_b32_e64 v4, v4, v2, s[68:69]
	v_cndmask_b32_e64 v2, 0, 1, s[0:1]
	v_cmp_ne_u32_e32 vcc, 0, v2
	v_cmp_ne_u32_e64 s[0:1], 0, v164
	v_readlane_b32 s71, v255, 29
	v_lshrrev_b64 v[2:3], v56, vcc
	v_cmp_ge_u32_e32 vcc, v164, v144
	s_and_b64 s[0:1], s[0:1], vcc
	v_cndmask_b32_e64 v4, v4, v2, s[70:71]
	v_cndmask_b32_e64 v2, 0, 1, s[0:1]
	v_cmp_ne_u32_e32 vcc, 0, v2
	v_readlane_b32 s72, v255, 30
	v_cmp_ne_u32_e64 s[0:1], 0, v163
	v_lshrrev_b64 v[2:3], v56, vcc
	v_cmp_ge_u32_e32 vcc, v163, v144
	v_readlane_b32 s73, v255, 31
	s_and_b64 s[0:1], s[0:1], vcc
	v_readlane_b32 s42, v255, 32
	v_cndmask_b32_e64 v4, v4, v2, s[72:73]
	v_cndmask_b32_e64 v2, 0, 1, s[0:1]
	v_cmp_ne_u32_e32 vcc, 0, v2
	v_cmp_ne_u32_e64 s[0:1], 0, v166
	v_readlane_b32 s43, v255, 33
	v_lshrrev_b64 v[2:3], v56, vcc
	v_cmp_ge_u32_e32 vcc, v166, v144
	s_and_b64 s[0:1], s[0:1], vcc
	v_cndmask_b32_e64 v4, v4, v2, s[42:43]
	v_cndmask_b32_e64 v2, 0, 1, s[0:1]
	v_cmp_ne_u32_e32 vcc, 0, v2
	v_readlane_b32 s34, v255, 34
	v_cmp_ne_u32_e64 s[0:1], 0, v165
	v_lshrrev_b64 v[2:3], v56, vcc
	v_cmp_ge_u32_e32 vcc, v165, v144
	v_readlane_b32 s35, v255, 35
	s_and_b64 s[0:1], s[0:1], vcc
	v_readlane_b32 s52, v255, 36
	v_cndmask_b32_e64 v4, v4, v2, s[34:35]
	v_cndmask_b32_e64 v2, 0, 1, s[0:1]
	v_cmp_ne_u32_e32 vcc, 0, v2
	v_cmp_ne_u32_e64 s[0:1], 0, v168
	v_readlane_b32 s53, v255, 37
	v_lshrrev_b64 v[2:3], v56, vcc
	v_cmp_ge_u32_e32 vcc, v168, v144
	s_and_b64 s[0:1], s[0:1], vcc
	v_cndmask_b32_e64 v4, v4, v2, s[52:53]
	v_cndmask_b32_e64 v2, 0, 1, s[0:1]
	v_cmp_ne_u32_e32 vcc, 0, v2
	v_readlane_b32 s90, v255, 38
	v_cmp_ne_u32_e64 s[0:1], 0, v167
	v_lshrrev_b64 v[2:3], v56, vcc
	v_cmp_ge_u32_e32 vcc, v167, v144
	v_readlane_b32 s91, v255, 39
	s_and_b64 s[0:1], s[0:1], vcc
	v_readlane_b32 s28, v255, 40
	v_cndmask_b32_e64 v4, v4, v2, s[90:91]
	v_cndmask_b32_e64 v2, 0, 1, s[0:1]
	v_cmp_ne_u32_e32 vcc, 0, v2
	v_cmp_ne_u32_e64 s[0:1], 0, v170
	v_readlane_b32 s29, v255, 41
	v_lshrrev_b64 v[2:3], v56, vcc
	v_cmp_ge_u32_e32 vcc, v170, v144
	s_and_b64 s[0:1], s[0:1], vcc
	v_cndmask_b32_e64 v4, v4, v2, s[28:29]
	v_cndmask_b32_e64 v2, 0, 1, s[0:1]
	v_cmp_ne_u32_e32 vcc, 0, v2
	v_readlane_b32 s54, v255, 42
	v_cmp_ne_u32_e64 s[0:1], 0, v169
	v_lshrrev_b64 v[2:3], v56, vcc
	v_cmp_ge_u32_e32 vcc, v169, v144
	v_readlane_b32 s55, v255, 43
	s_and_b64 s[0:1], s[0:1], vcc
	v_readlane_b32 s94, v255, 44
	v_cndmask_b32_e64 v4, v4, v2, s[54:55]
	v_cndmask_b32_e64 v2, 0, 1, s[0:1]
	v_cmp_ne_u32_e32 vcc, 0, v2
	v_cmp_ne_u32_e64 s[0:1], 0, v172
	v_readlane_b32 s95, v255, 45
	v_lshrrev_b64 v[2:3], v56, vcc
	v_cmp_ge_u32_e32 vcc, v172, v144
	s_and_b64 s[0:1], s[0:1], vcc
	v_cndmask_b32_e64 v4, v4, v2, s[94:95]
	v_cndmask_b32_e64 v2, 0, 1, s[0:1]
	v_cmp_ne_u32_e32 vcc, 0, v2
	v_readlane_b32 s2, v255, 46
	v_cmp_ne_u32_e64 s[0:1], 0, v171
	v_lshrrev_b64 v[2:3], v56, vcc
	v_cmp_ge_u32_e32 vcc, v171, v144
	v_readlane_b32 s3, v255, 47
	s_and_b64 s[0:1], s[0:1], vcc
	v_readlane_b32 s4, v255, 48
	v_cndmask_b32_e64 v4, v4, v2, s[2:3]
	v_cndmask_b32_e64 v2, 0, 1, s[0:1]
	v_cmp_ne_u32_e32 vcc, 0, v2
	v_cmp_ne_u32_e64 s[0:1], 0, v174
	v_readlane_b32 s5, v255, 49
	v_lshrrev_b64 v[2:3], v56, vcc
	v_cmp_ge_u32_e32 vcc, v174, v144
	s_and_b64 s[0:1], s[0:1], vcc
	v_cndmask_b32_e64 v4, v4, v2, s[4:5]
	v_cndmask_b32_e64 v2, 0, 1, s[0:1]
	v_cmp_ne_u32_e32 vcc, 0, v2
	v_readlane_b32 s20, v255, 50
	v_cmp_ne_u32_e64 s[0:1], 0, v173
	v_lshrrev_b64 v[2:3], v56, vcc
	v_cmp_ge_u32_e32 vcc, v173, v144
	v_readlane_b32 s21, v255, 51
	s_and_b64 s[0:1], s[0:1], vcc
	v_readlane_b32 s64, v255, 52
	v_cndmask_b32_e64 v4, v4, v2, s[20:21]
	v_cndmask_b32_e64 v2, 0, 1, s[0:1]
	v_cmp_ne_u32_e32 vcc, 0, v2
	v_cmp_ne_u32_e64 s[0:1], 0, v182
	v_readlane_b32 s65, v255, 53
	v_lshrrev_b64 v[2:3], v56, vcc
	v_cmp_ge_u32_e32 vcc, v182, v144
	s_and_b64 s[0:1], s[0:1], vcc
	v_cndmask_b32_e64 v4, v4, v2, s[64:65]
	v_cndmask_b32_e64 v2, 0, 1, s[0:1]
	v_cmp_ne_u32_e32 vcc, 0, v2
	v_readlane_b32 s74, v255, 54
	v_cmp_ne_u32_e64 s[0:1], 0, v175
	v_lshrrev_b64 v[2:3], v56, vcc
	v_cmp_ge_u32_e32 vcc, v175, v144
	v_readlane_b32 s75, v255, 55
	s_and_b64 s[0:1], s[0:1], vcc
	s_nop 0
	v_cndmask_b32_e64 v4, v4, v2, s[74:75]
	v_cndmask_b32_e64 v2, 0, 1, s[0:1]
	v_cmp_ne_u32_e32 vcc, 0, v2
	v_cmp_ne_u32_e64 s[0:1], 0, v184
	s_nop 0
	v_lshrrev_b64 v[2:3], v56, vcc
	v_cmp_ge_u32_e32 vcc, v184, v144
	s_and_b64 s[0:1], s[0:1], vcc
	v_cndmask_b32_e64 v5, 0, v2, s[36:37]
	v_cndmask_b32_e64 v2, 0, 1, s[0:1]
	v_cmp_ne_u32_e32 vcc, 0, v2
	v_cmp_ne_u32_e64 s[0:1], 0, v183
	s_nop 0
	v_lshrrev_b64 v[2:3], v56, vcc
	v_cmp_ge_u32_e32 vcc, v183, v144
	s_and_b64 s[0:1], s[0:1], vcc
; DI void indexer_phase(const u16* __restrict__ P, unsigned* __restrict__ mask) {
;     ...
;     unsigned w0 = 0u, w1 = 0u;
; #pragma unroll
;     for (int kb = 0; kb < 64; ++kb) {
;       const bool pred = (sc[kb] >= T) && (sc[kb] != 0u);
;       const unsigned long long bal = __ballot(pred);
;       const unsigned wd = (unsigned)(bal >> (32 * hi));
;       if ((kb & 31) == r32) { if (kb < 32) w0 = wd; else w1 = wd; }
;     }
	v_cndmask_b32_e64 v5, v5, v2, s[38:39]
	v_cndmask_b32_e64 v2, 0, 1, s[0:1]
	v_cmp_ne_u32_e32 vcc, 0, v2
	v_cmp_ne_u32_e64 s[0:1], 0, v186
	s_nop 0
	v_lshrrev_b64 v[2:3], v56, vcc
	v_cmp_ge_u32_e32 vcc, v186, v144
	s_and_b64 s[0:1], s[0:1], vcc
	v_cndmask_b32_e64 v5, v5, v2, s[40:41]
	v_cndmask_b32_e64 v2, 0, 1, s[0:1]
	v_cmp_ne_u32_e32 vcc, 0, v2
	v_cmp_ne_u32_e64 s[0:1], 0, v185
	s_nop 0
	v_lshrrev_b64 v[2:3], v56, vcc
	v_cmp_ge_u32_e32 vcc, v185, v144
	s_and_b64 s[0:1], s[0:1], vcc
	v_cndmask_b32_e64 v5, v5, v2, s[44:45]
	v_cndmask_b32_e64 v2, 0, 1, s[0:1]
	v_cmp_ne_u32_e32 vcc, 0, v2
	v_cmp_ne_u32_e64 s[0:1], 0, v188
	s_nop 0
	v_lshrrev_b64 v[2:3], v56, vcc
	v_cmp_ge_u32_e32 vcc, v188, v144
	s_and_b64 s[0:1], s[0:1], vcc
	v_cndmask_b32_e64 v5, v5, v2, s[46:47]
	v_cndmask_b32_e64 v2, 0, 1, s[0:1]
	v_cmp_ne_u32_e32 vcc, 0, v2
	v_cmp_ne_u32_e64 s[0:1], 0, v187
	s_nop 0
	v_lshrrev_b64 v[2:3], v56, vcc
	v_cmp_ge_u32_e32 vcc, v187, v144
	s_and_b64 s[0:1], s[0:1], vcc
	v_cndmask_b32_e64 v5, v5, v2, s[48:49]
	v_cndmask_b32_e64 v2, 0, 1, s[0:1]
	v_cmp_ne_u32_e32 vcc, 0, v2
	v_cmp_ne_u32_e64 s[0:1], 0, v190
	s_nop 0
	v_lshrrev_b64 v[2:3], v56, vcc
	v_cmp_ge_u32_e32 vcc, v190, v144
	s_and_b64 s[0:1], s[0:1], vcc
	v_cndmask_b32_e64 v5, v5, v2, s[50:51]
	v_cndmask_b32_e64 v2, 0, 1, s[0:1]
	v_cmp_ne_u32_e32 vcc, 0, v2
	v_cmp_ne_u32_e64 s[0:1], 0, v189
	s_nop 0
	v_lshrrev_b64 v[2:3], v56, vcc
	v_cmp_ge_u32_e32 vcc, v189, v144
	s_and_b64 s[0:1], s[0:1], vcc
	v_cndmask_b32_e64 v5, v5, v2, s[18:19]
	v_cndmask_b32_e64 v2, 0, 1, s[0:1]
	v_cmp_ne_u32_e32 vcc, 0, v2
	v_cmp_ne_u32_e64 s[0:1], 0, v192
	s_nop 0
	v_lshrrev_b64 v[2:3], v56, vcc
	v_cmp_ge_u32_e32 vcc, v192, v144
	s_and_b64 s[0:1], s[0:1], vcc
	v_cndmask_b32_e64 v5, v5, v2, s[22:23]
	v_cndmask_b32_e64 v2, 0, 1, s[0:1]
	v_cmp_ne_u32_e32 vcc, 0, v2
	v_cmp_ne_u32_e64 s[0:1], 0, v191
	s_nop 0
	v_lshrrev_b64 v[2:3], v56, vcc
	v_cmp_ge_u32_e32 vcc, v191, v144
	s_and_b64 s[0:1], s[0:1], vcc
	v_cndmask_b32_e64 v5, v5, v2, s[24:25]
	v_cndmask_b32_e64 v2, 0, 1, s[0:1]
	v_cmp_ne_u32_e32 vcc, 0, v2
	v_cmp_ne_u32_e64 s[0:1], 0, v194
	s_nop 0
	v_lshrrev_b64 v[2:3], v56, vcc
	v_cmp_ge_u32_e32 vcc, v194, v144
	s_and_b64 s[0:1], s[0:1], vcc
	v_cndmask_b32_e64 v5, v5, v2, s[26:27]
	v_cndmask_b32_e64 v2, 0, 1, s[0:1]
	v_cmp_ne_u32_e32 vcc, 0, v2
	v_cmp_ne_u32_e64 s[0:1], 0, v193
	s_nop 0
	v_lshrrev_b64 v[2:3], v56, vcc
	v_cmp_ge_u32_e32 vcc, v193, v144
	s_and_b64 s[0:1], s[0:1], vcc
	v_cndmask_b32_e64 v5, v5, v2, s[30:31]
	v_cndmask_b32_e64 v2, 0, 1, s[0:1]
	v_cmp_ne_u32_e32 vcc, 0, v2
	v_cmp_ne_u32_e64 s[0:1], 0, v196
	s_nop 0
	v_lshrrev_b64 v[2:3], v56, vcc
	v_cmp_ge_u32_e32 vcc, v196, v144
	s_and_b64 s[0:1], s[0:1], vcc
	v_cndmask_b32_e64 v5, v5, v2, s[8:9]
	v_cndmask_b32_e64 v2, 0, 1, s[0:1]
	v_cmp_ne_u32_e32 vcc, 0, v2
	v_cmp_ne_u32_e64 s[0:1], 0, v195
	v_readlane_b32 s8, v255, 56
	v_lshrrev_b64 v[2:3], v56, vcc
	v_cmp_ge_u32_e32 vcc, v195, v144
	s_and_b64 s[0:1], s[0:1], vcc
	v_cndmask_b32_e64 v5, v5, v2, s[10:11]
	v_cndmask_b32_e64 v2, 0, 1, s[0:1]
	v_cmp_ne_u32_e32 vcc, 0, v2
	v_cmp_ne_u32_e64 s[0:1], 0, v198
	v_readlane_b32 s9, v255, 57
	v_lshrrev_b64 v[2:3], v56, vcc
	v_cmp_ge_u32_e32 vcc, v198, v144
	s_and_b64 s[0:1], s[0:1], vcc
	v_cndmask_b32_e64 v5, v5, v2, s[12:13]
	v_cndmask_b32_e64 v2, 0, 1, s[0:1]
	v_cmp_ne_u32_e32 vcc, 0, v2
	v_cmp_ne_u32_e64 s[0:1], 0, v197
	s_nop 0
	v_lshrrev_b64 v[2:3], v56, vcc
	v_cmp_ge_u32_e32 vcc, v197, v144
	s_and_b64 s[0:1], s[0:1], vcc
	v_cndmask_b32_e64 v5, v5, v2, s[14:15]
	v_cndmask_b32_e64 v2, 0, 1, s[0:1]
	v_cmp_ne_u32_e32 vcc, 0, v2
	v_cmp_ne_u32_e64 s[0:1], 0, v200
	s_nop 0
	v_lshrrev_b64 v[2:3], v56, vcc
	v_cmp_ge_u32_e32 vcc, v200, v144
	s_and_b64 s[0:1], s[0:1], vcc
	v_cndmask_b32_e64 v5, v5, v2, s[66:67]
	v_cndmask_b32_e64 v2, 0, 1, s[0:1]
	v_cmp_ne_u32_e32 vcc, 0, v2
	v_cmp_ne_u32_e64 s[0:1], 0, v199
	s_nop 0
	v_lshrrev_b64 v[2:3], v56, vcc
	v_cmp_ge_u32_e32 vcc, v199, v144
	s_and_b64 s[0:1], s[0:1], vcc
	v_cndmask_b32_e64 v5, v5, v2, s[68:69]
; DI void indexer_phase(const u16* __restrict__ P, unsigned* __restrict__ mask) {
;     ...
;     unsigned w0 = 0u, w1 = 0u;
; #pragma unroll
;     for (int kb = 0; kb < 64; ++kb) {
;       const bool pred = (sc[kb] >= T) && (sc[kb] != 0u);
;       const unsigned long long bal = __ballot(pred);
;       const unsigned wd = (unsigned)(bal >> (32 * hi));
;       if ((kb & 31) == r32) { if (kb < 32) w0 = wd; else w1 = wd; }
;     }
;     mask[(brow + tme) * 64 + r32] = w0;
;     mask[(brow + tme) * 64 + 32 + r32] = w1;
	v_cndmask_b32_e64 v2, 0, 1, s[0:1]
	v_cmp_ne_u32_e32 vcc, 0, v2
	v_cmp_ne_u32_e64 s[0:1], 0, v202
	s_nop 0
	v_lshrrev_b64 v[2:3], v56, vcc
	v_cmp_ge_u32_e32 vcc, v202, v144
	s_and_b64 s[0:1], s[0:1], vcc
	v_cndmask_b32_e64 v5, v5, v2, s[70:71]
	v_cndmask_b32_e64 v2, 0, 1, s[0:1]
	v_cmp_ne_u32_e32 vcc, 0, v2
	v_cmp_ne_u32_e64 s[0:1], 0, v201
	s_nop 0
	v_lshrrev_b64 v[2:3], v56, vcc
	v_cmp_ge_u32_e32 vcc, v201, v144
	s_and_b64 s[0:1], s[0:1], vcc
	v_cndmask_b32_e64 v5, v5, v2, s[72:73]
	v_cndmask_b32_e64 v2, 0, 1, s[0:1]
	v_cmp_ne_u32_e32 vcc, 0, v2
	v_cmp_ne_u32_e64 s[0:1], 0, v204
	s_nop 0
	v_lshrrev_b64 v[2:3], v56, vcc
	v_cmp_ge_u32_e32 vcc, v204, v144
	s_and_b64 s[0:1], s[0:1], vcc
	v_cndmask_b32_e64 v5, v5, v2, s[42:43]
	v_cndmask_b32_e64 v2, 0, 1, s[0:1]
	v_cmp_ne_u32_e32 vcc, 0, v2
	v_cmp_ne_u32_e64 s[0:1], 0, v203
	s_mov_b64 s[42:43], s[76:77]
	v_lshrrev_b64 v[2:3], v56, vcc
	v_cmp_ge_u32_e32 vcc, v203, v144
	s_and_b64 s[0:1], s[0:1], vcc
	v_cndmask_b32_e64 v5, v5, v2, s[34:35]
	v_cndmask_b32_e64 v2, 0, 1, s[0:1]
	v_cmp_ne_u32_e32 vcc, 0, v2
	v_cmp_ne_u32_e64 s[0:1], 0, v206
	v_readlane_b32 s76, v254, 37
	v_lshrrev_b64 v[2:3], v56, vcc
	v_cmp_ge_u32_e32 vcc, v206, v144
	s_and_b64 s[0:1], s[0:1], vcc
	v_cndmask_b32_e64 v5, v5, v2, s[52:53]
	v_cndmask_b32_e64 v2, 0, 1, s[0:1]
	v_cmp_ne_u32_e32 vcc, 0, v2
	v_cmp_ne_u32_e64 s[0:1], 0, v205
	s_mov_b64 s[52:53], s[96:97]
	v_lshrrev_b64 v[2:3], v56, vcc
	v_cmp_ge_u32_e32 vcc, v205, v144
	s_and_b64 s[0:1], s[0:1], vcc
	v_cndmask_b32_e64 v5, v5, v2, s[90:91]
	v_cndmask_b32_e64 v2, 0, 1, s[0:1]
	v_cmp_ne_u32_e32 vcc, 0, v2
	v_cmp_ne_u32_e64 s[0:1], 0, v236
	v_readlane_b32 s96, v254, 33
	v_lshrrev_b64 v[2:3], v56, vcc
	v_cmp_ge_u32_e32 vcc, v236, v144
	s_and_b64 s[0:1], s[0:1], vcc
	v_cndmask_b32_e64 v5, v5, v2, s[28:29]
	v_cndmask_b32_e64 v2, 0, 1, s[0:1]
	v_cmp_ne_u32_e32 vcc, 0, v2
	v_cmp_ne_u32_e64 s[0:1], 0, v207
	v_readlane_b32 s77, v254, 38
	v_lshrrev_b64 v[2:3], v56, vcc
	v_cmp_ge_u32_e32 vcc, v207, v144
	s_and_b64 s[0:1], s[0:1], vcc
	v_cndmask_b32_e64 v5, v5, v2, s[54:55]
	v_cndmask_b32_e64 v2, 0, 1, s[0:1]
	v_cmp_ne_u32_e32 vcc, 0, v2
	v_cmp_ne_u32_e64 s[0:1], 0, v238
	s_movk_i32 s34, 0xc00
	v_lshrrev_b64 v[2:3], v56, vcc
	v_cmp_ge_u32_e32 vcc, v238, v144
	s_and_b64 s[0:1], s[0:1], vcc
	v_cndmask_b32_e64 v5, v5, v2, s[94:95]
	v_cndmask_b32_e64 v2, 0, 1, s[0:1]
	v_cmp_ne_u32_e32 vcc, 0, v2
	v_cmp_ne_u32_e64 s[0:1], 0, v237
	s_mov_b64 s[90:91], s[16:17]
	v_lshrrev_b64 v[2:3], v56, vcc
	v_cmp_ge_u32_e32 vcc, v237, v144
	s_and_b64 s[0:1], s[0:1], vcc
	v_cndmask_b32_e64 v5, v5, v2, s[2:3]
	v_cndmask_b32_e64 v2, 0, 1, s[0:1]
	v_cmp_ne_u32_e32 vcc, 0, v2
	v_cmp_ne_u32_e64 s[0:1], 0, v240
	s_mov_b32 s28, s78
	v_lshrrev_b64 v[2:3], v56, vcc
	v_cmp_ge_u32_e32 vcc, v240, v144
	s_and_b64 s[0:1], s[0:1], vcc
	v_cndmask_b32_e64 v5, v5, v2, s[4:5]
	v_cndmask_b32_e64 v2, 0, 1, s[0:1]
	v_cmp_ne_u32_e32 vcc, 0, v2
	v_cmp_ne_u32_e64 s[0:1], 0, v239
	s_mov_b64 s[4:5], s[84:85]
	v_lshrrev_b64 v[2:3], v56, vcc
	v_cmp_ge_u32_e32 vcc, v239, v144
	s_and_b64 s[0:1], s[0:1], vcc
	v_cndmask_b32_e64 v5, v5, v2, s[20:21]
	v_cndmask_b32_e64 v2, 0, 1, s[0:1]
	v_cmp_ne_u32_e32 vcc, 0, v2
	v_cmp_ne_u32_e64 s[0:1], 0, v18
	v_readlane_b32 s97, v254, 34
	v_lshrrev_b64 v[2:3], v56, vcc
	v_cmp_ge_u32_e32 vcc, v18, v144
	s_and_b64 s[0:1], s[0:1], vcc
	v_cndmask_b32_e64 v5, v5, v2, s[64:65]
	v_cndmask_b32_e64 v2, 0, 1, s[0:1]
	v_cmp_ne_u32_e32 vcc, 0, v2
	s_mov_b32 s35, s86
	s_mov_b32 s84, s79
	v_lshrrev_b64 v[2:3], v56, vcc
	v_cndmask_b32_e64 v5, v5, v2, s[74:75]
	v_add_u32_e32 v2, v127, v126
	v_mov_b32_e32 v3, v1
	v_lshlrev_b64 v[2:3], 8, v[2:3]
	v_readlane_b32 s74, v254, 35
	v_lshl_add_u64 v[2:3], v[58:59], 0, v[2:3]
	v_readlane_b32 s75, v254, 36
	s_mov_b32 s55, s59
	s_mov_b32 s3, s63
	s_movk_i32 s20, 0x600
	s_mov_b32 s21, 0x41000000
	s_mov_b32 s64, 0x3e38aa3b
	s_movk_i32 s2, 0x2000
	global_store_dword v[2:3], v4, off
	global_store_dword v[2:3], v5, off offset:128
	s_branch .LBB0_845
